# v30 + dynamic balance between the two XCDs of a batch: a CU whose own per-XCD unit queue is empty steals units from the sibling XCD queue before taking pool items (separate per-XCD pool counter)
# speedup vs baseline: 1.0213x; 1.0061x over previous
; __device__ __forceinline__ void unit_of(int idx,volatile __attribute__((address_space(3))) const unsigned*stats,AttnUnit&u){
;     const int jq=63-(idx>>5), r=idx&31, b=r>>3, h=7-(r&7);
;     u.b=b; u.h=h; u.s2=__builtin_amdgcn_exp2f(-(float)(h+1))*1.4426950408889634f; u.jq=jq;
; template<int THRL,class Extra> __device__ __forceinline__ void attn_phase(char*lds,const AttnTensors&T,const unsigned*stats,unsigned*queue,volatile __attribute__((address_space(3))) unsigned*qw,const Extra&X){
;     ...
;   { int t_=threadIdx.x; asm volatile("":"+v"(t_));
;     if(t_<256)sl[t_]=__hip_atomic_load(stats+t_,__ATOMIC_RELAXED,__HIP_MEMORY_SCOPE_AGENT); }
;   if(threadIdx.x==0)nxt=__hip_atomic_fetch_add(queue,1u,__ATOMIC_RELAXED,__HIP_MEMORY_SCOPE_AGENT);
;   for(;;){
;     if(threadIdx.x==0)qw[0]=nxt;
;     asm volatile("s_waitcnt vmcnt(0) lgkmcnt(0)\n\ts_barrier":::"memory");
;     idx=__builtin_amdgcn_readfirstlane((int)qw[0]);
;     asm volatile("s_waitcnt lgkmcnt(0)\n\ts_barrier":::"memory");
;     if(idx>=N_UNITS)break;
;     if(threadIdx.x==0)nxt=__hip_atomic_fetch_add(queue,1u,__ATOMIC_RELAXED,__HIP_MEMORY_SCOPE_AGENT);
;     AttnUnit u; unit_of(idx,sl,u);
.LBB0_265:
	s_or_b64 exec, exec, s[10:11]
	s_waitcnt vmcnt(0)
	v_readfirstlane_b32 s0, v2
	s_nop 1
	v_add_u32_e32 v237, s0, v1
	s_getreg_b32 s100, hwreg(HW_REG_XCC_ID, 0, 4)
	s_and_b32 s100, s100, 7
	s_cmp_lt_u32 s0, 0x100
	s_cbranch_scc1 .Lq_map_1
	s_xor_b32 s0, s54, 4
	s_mov_b32 s1, s55
	v_mov_b32_e32 v2, 1
	global_atomic_add v2, v0, v2, s[0:1] sc0
	s_waitcnt vmcnt(0)
	v_readfirstlane_b32 s0, v2
	s_xor_b32 s100, s100, 1
	s_cmp_lt_u32 s0, 0x100
	s_cbranch_scc1 .Lq_map_1
	s_xor_b32 s100, s100, 1
	v_mov_b32_e32 v2, 1
	global_atomic_add v2, v0, v2, s[54:55] offset:32 sc0
	s_waitcnt vmcnt(0)
	v_readfirstlane_b32 s0, v2
	s_lshl_b32 s100, s100, 5
	s_add_i32 s100, s100, s0
	s_lshr_b32 s0, s0, 5
	s_lshl_b32 s0, s0, 8
	s_add_i32 s100, s100, s0
	s_addk_i32 s100, 0x800
	v_mov_b32_e32 v237, s100
	s_branch .Lq_done_1
.Lq_map_1:
	s_lshr_b32 s101, s0, 6
	s_lshl_b32 s101, s101, 2
	s_and_b32 s1, s100, 1
	s_mul_i32 s1, s1, 0x1122
	s_xor_b32 s1, s1, 0x1267
	s_lshr_b32 s1, s1, s101
	s_and_b32 s1, s1, 15
	s_sub_i32 s1, 7, s1
	s_and_b32 s101, s100, 6
	s_lshl_b32 s101, s101, 2
	s_or_b32 s1, s1, s101
	s_and_b32 s0, s0, 63
	s_lshl_b32 s0, s0, 5
	s_or_b32 s0, s0, s1
	v_mov_b32_e32 v237, s0
.Lq_done_1:
.LBB0_266:
	s_or_b64 exec, exec, s[4:5]
	s_add_u32 s68, s8, 0x1ec00000
	s_addc_u32 s69, s9, 0
	s_add_u32 s70, s8, 0x22c00000
	s_addc_u32 s72, s9, 0
	s_add_u32 s73, s8, 0x26c00000
	s_addc_u32 s74, s9, 0
	s_add_u32 s75, s8, 0x3ac00000
	s_addc_u32 s76, s9, 0
	s_lshl_b32 s0, s52, 10
	s_ashr_i32 s1, s0, 31
	s_lshl_b64 s[0:1], s[0:1], 2
	s_waitcnt lgkmcnt(0)
	s_add_u32 s77, s6, s0
	s_addc_u32 s78, s7, s1
	s_branch .LBB0_269

; template<int THRL,class Extra> __device__ __forceinline__ void attn_phase(char*lds,const AttnTensors&T,const unsigned*stats,unsigned*queue,volatile __attribute__((address_space(3))) unsigned*qw,const Extra&X){
;     ...
;     if(threadIdx.x==0)nxt=__hip_atomic_fetch_add(queue,1u,__ATOMIC_RELAXED,__HIP_MEMORY_SCOPE_AGENT);
;     AttnUnit u; unit_of(idx,sl,u);
.LBB0_275:
	s_or_b64 exec, exec, s[6:7]
	s_waitcnt vmcnt(0)
	v_readfirstlane_b32 s0, v2
	s_nop 1
	v_add_u32_e32 v237, s0, v1
	s_getreg_b32 s100, hwreg(HW_REG_XCC_ID, 0, 4)
	s_and_b32 s100, s100, 7
	s_cmp_lt_u32 s0, 0x100
	s_cbranch_scc1 .Lq_map_2
	s_xor_b32 s0, s54, 4
	s_mov_b32 s1, s55
	v_mov_b32_e32 v2, 1
	global_atomic_add v2, v0, v2, s[0:1] sc0
	s_waitcnt vmcnt(0)
	v_readfirstlane_b32 s0, v2
	s_xor_b32 s100, s100, 1
	s_cmp_lt_u32 s0, 0x100
	s_cbranch_scc1 .Lq_map_2
	s_xor_b32 s100, s100, 1
	v_mov_b32_e32 v2, 1
	global_atomic_add v2, v0, v2, s[54:55] offset:32 sc0
	s_waitcnt vmcnt(0)
	v_readfirstlane_b32 s0, v2
	s_lshl_b32 s100, s100, 5
	s_add_i32 s100, s100, s0
	s_lshr_b32 s0, s0, 5
	s_lshl_b32 s0, s0, 8
	s_add_i32 s100, s100, s0
	s_addk_i32 s100, 0x800
	v_mov_b32_e32 v237, s100
	s_branch .Lq_done_2

; template<int THRL> __device__ __forceinline__ void attn_unit(int b,int h,float s2,int jq,int t0,const bf16*Q,const bf16*__restrict__ K,const bf16*__restrict__ V,bf16*MIXo,const float*gh,volatile __attribute__((address_space(3))) const float*lamw,char*shm){
;   int tid_=threadIdx.x; asm volatile("":"+v"(tid_)); const int tid=tid_,lane=tid&63,r32=lane&31,hi=lane>>5; const int wid=__builtin_amdgcn_readfirstlane(tid>>6);
;   const int wm=wid>>2, wq=wid&3;
;   const long rowbase=(long)b*SEQ; const int q0=jq*128;
;   const bf16*Qw=Q+(rowbase+q0+wq*QBLK)*DM+(h*2+wm)*64;
;   const bf16*Kh=K+(rowbase+(long)t0*KVBLK)*DM+h*128,*Vh=V+(rowbase+(long)t0*KVBLK)*DM+h*128;
;   const unsigned lds0=(unsigned)(uintptr_t)shm;
;   float*wsf=(float*)(shm+LDS_WS)+wid*64;
;   const unsigned koff=(unsigned)(lane*DM+wid*8)*2u;
;   const unsigned voff=(unsigned)((16*(wid&3)+(lane>>2))*DM+(wid>>2)*32+(lane&3)*8)*2u;
;   const unsigned kdst=lds0+LDS_K+wid*1024, vdst=lds0+LDS_V+wid*1024;
;     ...
;   const int vb0=(int)(lds0+LDS_V)+((lane>>4)&1)*32+(lane&3)*8+(4*hi+((lane&15)>>2))*64;
;   const char*Kbase=shm+LDS_K+wm*KRING; bf16x8 kf[8];
;   const lds_cptr shm3=(lds_cptr)shm; const lds_cptr kp0=shm3+LDS_K+wm*KRING+hi*1024+r32*16; const lds_cptr vp0=shm3+LDS_V+((lane>>4)&1)*32+(lane&3)*8+(4*hi+((lane&15)>>2))*64;
;   const int NT=(jq==0?4:2*jq+2)-t0, tb=2*jq-t0;
;   DMA_K(0,0);DMA_V(0,0);DMA_K(1,SLOTB);
;   bf16x8 qr[4];
;   #pragma unroll
;   for(int d0=0;d0<4;++d0)qr[d0]=*reinterpret_cast<const bf16x8*>(&Qw[(long)r32*DM+d0*16+hi*8]);
; __device__ __forceinline__ void unit_of(int idx,volatile __attribute__((address_space(3))) const unsigned*stats,AttnUnit&u){
;     const int jq=63-(idx>>5), r=idx&31, b=r>>3, h=7-(r&7);
;     u.b=b; u.h=h; u.s2=__builtin_amdgcn_exp2f(-(float)(h+1))*1.4426950408889634f; u.jq=jq;
;     float qk=0.f;
; #pragma unroll
;     for(int m=0;m<2;++m){ volatile __attribute__((address_space(3))) const unsigned*sp=stats+(b*16+h*2+m)*4;
;       const float q2=__uint_as_float(sp[0])+__uint_as_float(sp[1]), k2=__uint_as_float(sp[2])+__uint_as_float(sp[3]);
;       qk=fmaxf(qk,q2*k2); }
;     const float dskip=(154.f+2.05f*sqrtf(qk))/u.s2;
;     const float tf=floorf(((float)(jq*128)-dskip)*(1.0f/64.0f));
;     int t0=tf>0.f?(int)tf:0; t0&=~1; const int cap=jq>0?2*jq-2:0; if(t0>cap)t0=cap; u.t0=t0;
; }
.Lq_done_2:
.LBB0_276:
	s_or_b64 exec, exec, s[4:5]
	s_and_b32 s4, s71, 7
	s_bfe_u32 s2, s71, 0x20003
	s_xor_b32 s79, s4, 7
	s_sub_i32 s4, 8, s4
	v_cvt_f32_ubyte0_e32 v1, s4
	s_lshl_b32 s4, s2, 8
	s_lshl_b32 s5, s79, 5
	s_add_i32 s4, s4, 0
	s_add_i32 s4, s4, s5
	s_add_i32 s4, s4, 0x22400
	v_exp_f32_e64 v35, -v1
	v_mov_b32_e32 v1, s4
	ds_read_b32 v2, v1
	ds_read_b32 v4, v1 offset:4
	ds_read_b32 v3, v1 offset:8
	ds_read_b32 v5, v1 offset:12
	s_mov_b32 s50, 0x40033333
	s_mov_b32 s51, 0x3fb8aa3b
	s_ashr_i32 s0, s71, 5
	s_sub_i32 s1, 63, s0
	s_waitcnt lgkmcnt(0)
	v_pk_add_f32 v[2:3], v[2:3], v[4:5]
	v_mov_b32_e32 v210, v253
	v_mul_f32_e32 v6, v2, v3
	ds_read_b32 v2, v1 offset:16
	ds_read_b32 v4, v1 offset:20
	ds_read_b32 v3, v1 offset:24
	ds_read_b32 v5, v1 offset:28
	s_mov_b32 s11, s25
	v_and_b32_e32 v240, 63, v253
	v_and_b32_e32 v238, 31, v253
	s_waitcnt lgkmcnt(0)
	v_pk_add_f32 v[2:3], v[2:3], v[4:5]
	v_mov_b32_e32 v220, 0x358637bd
	v_mul_f32_e32 v1, v2, v3
	v_max3_f32 v1, v6, 0, v1
	v_cmp_gt_f32_e32 vcc, s47, v1
	v_mul_f32_e32 v2, 0x4f800000, v1
	v_mov_b32_e32 v222, v226
	v_cndmask_b32_e32 v1, v1, v2, vcc
	v_sqrt_f32_e32 v2, v1
	v_mov_b32_e32 v208, v224
	v_mov_b32_e32 v224, v223
	v_mov_b32_e32 v234, v218
	v_add_u32_e32 v3, -1, v2
	v_fma_f32 v4, -v3, v2, v1
	v_cmp_ge_f32_e64 s[4:5], 0, v4
	v_add_u32_e32 v4, 1, v2
	s_nop 0
	v_cndmask_b32_e64 v3, v2, v3, s[4:5]
	v_fma_f32 v2, -v4, v2, v1
	v_cmp_lt_f32_e64 s[4:5], 0, v2
	s_nop 1
	v_cndmask_b32_e64 v2, v3, v4, s[4:5]
	v_mul_f32_e32 v3, 0x37800000, v2
	v_cndmask_b32_e32 v2, v2, v3, vcc
	v_cmp_class_f32_e32 vcc, v1, v209
	s_nop 1
	v_cndmask_b32_e32 v34, v2, v1, vcc
	v_pk_mul_f32 v[214:215], v[34:35], s[50:51]
	s_nop 0
	v_add_f32_e32 v1, 0x431a0000, v214
	v_div_scale_f32 v2, s[4:5], v215, v215, v1
	v_rcp_f32_e32 v3, v2
	s_lshl_b32 s5, s1, 7
	s_lshl_b32 s1, s1, 1
	s_add_i32 s4, s1, -2
	v_fma_f32 v4, -v2, v3, 1.0
	v_fmac_f32_e32 v3, v4, v3
	v_div_scale_f32 v4, vcc, v1, v215, v1
	v_mul_f32_e32 v5, v4, v3
	v_fma_f32 v6, -v2, v5, v4
	v_fmac_f32_e32 v5, v6, v3
	v_fma_f32 v2, -v2, v5, v4
	v_div_fmas_f32 v2, v2, v3, v5
	v_div_fixup_f32 v1, v2, v215, v1
	v_cvt_f32_u32_e32 v2, s5
	s_cmp_lt_i32 s0, 63
	s_cselect_b32 s4, s4, 0
	s_lshl_b32 s7, s2, 13
	v_sub_f32_e32 v1, v2, v1
	v_mul_f32_e32 v1, 0x3c800000, v1
	v_floor_f32_e32 v1, v1
	v_max_f32_e32 v1, 0, v1
	v_cvt_i32_f32_e32 v1, v1
	s_add_i32 s7, s7, s5
	v_lshlrev_b32_e32 v2, 11, v240
	v_lshlrev_b32_e32 v3, 3, v253
	v_and_b32_e32 v1, -2, v1
	v_min_i32_e32 v1, s4, v1
	v_readfirstlane_b32 s4, v253
	s_ashr_i32 s82, s4, 6
	s_and_b32 s81, s82, 3
	s_lshl_b32 s5, s81, 5
	s_or_b32 s10, s7, s5
	s_ashr_i32 s80, s4, 8
	s_lshl_b64 s[12:13], s[10:11], 11
	s_add_u32 s7, s68, s12
	s_addc_u32 s16, s69, s13
	s_lshl_b32 s12, s79, 7
	s_lshl_b32 s22, s80, 6
	s_add_i32 s12, s22, s12
	s_ashr_i32 s13, s12, 31
	s_lshl_b64 s[12:13], s[12:13], 1
	v_readfirstlane_b32 s6, v1
	s_add_u32 s18, s7, s12
	s_addc_u32 s19, s16, s13
	s_ashr_i32 s7, s6, 31
	s_lshl_b64 s[12:13], s[6:7], 16
	s_lshl_b32 s2, s2, 23
	s_add_u32 s12, s12, s2
	s_addc_u32 s13, s13, 0
	s_lshl_b64 s[16:17], s[12:13], 1
	s_add_u32 s2, s70, s16
	s_addc_u32 s7, s72, s17
	s_lshl_b32 s24, s79, 8
	s_add_u32 s12, s2, s24
	s_addc_u32 s13, s7, 0
	s_add_u32 s2, s73, s16
	s_addc_u32 s7, s74, s17
	s_add_u32 s16, s2, s24
	v_lshl_add_u32 v245, s82, 4, v2
	v_lshlrev_b32_e32 v2, 8, v253
	v_and_b32_e32 v241, 24, v3
	s_movk_i32 s2, 0x3c00
	s_addc_u32 s17, s7, 0
	v_and_or_b32 v2, v2, s2, v241
	s_lshl_b32 s2, s81, 15
	s_add_i32 s2, s2, s22
	v_lshl_add_u32 v246, v2, 1, s2
	s_lshl_b32 s2, s82, 10
	s_cmp_lg_u32 0, -1
	s_cselect_b32 s7, 0, 0
	s_add_i32 s84, s2, s7
	s_mov_b32 m0, s84
	s_nop 0
	global_load_lds_dwordx4 v245, s[12:13]
	s_mul_i32 s7, s80, 0x6000
	v_add_u32_e32 v247, 0x80, v245
	s_add_i32 s86, s84, 0x6000
	s_mov_b32 m0, s86
	s_nop 0
	global_load_lds_dwordx4 v247, s[12:13]
	s_add_i32 s85, s84, 0xc000
	s_add_i32 s22, s7, 0
	s_mov_b32 m0, s85
	s_nop 0
	global_load_lds_dwordx4 v246, s[16:17]
	s_add_i32 s7, s84, 0xe000
	v_add_u32_e32 v248, 0x80, v246
	s_mov_b32 m0, s7
	s_nop 0
	global_load_lds_dwordx4 v248, s[16:17]
	s_add_u32 s28, s12, 0x20000
	v_bfe_u32 v1, v253, 5, 1
	s_addc_u32 s29, s13, 0
	s_add_i32 s7, s84, 0x2000
	s_mov_b32 m0, s7
	s_nop 0
	global_load_lds_dwordx4 v245, s[28:29]
	v_lshlrev_b32_e32 v3, 11, v238
	v_lshlrev_b32_e32 v243, 2, v1
	v_lshlrev_b32_e32 v239, 10, v1
	s_add_i32 s7, s84, 0x8000
	s_mov_b32 m0, s7
	s_nop 0
	global_load_lds_dwordx4 v247, s[28:29]
	v_lshl_or_b32 v1, v1, 4, v3
	global_load_dwordx4 v[164:167], v1, s[18:19]
	global_load_dwordx4 v[156:159], v1, s[18:19] offset:32
	global_load_dwordx4 v[148:151], v1, s[18:19] offset:64
	global_load_dwordx4 v[144:147], v1, s[18:19] offset:96
	s_lshl_b32 s7, s6, 6
	s_add_u32 s18, s12, 0x40000
	s_addc_u32 s19, s13, 0
	s_add_i32 s24, s84, 0x4000
	s_mov_b32 m0, s24
	s_nop 0
	global_load_lds_dwordx4 v245, s[18:19]
	v_lshlrev_b32_e32 v2, 4, v238
	s_add_i32 s24, s84, 0xa000
	s_mov_b32 m0, s24
	s_nop 0
	global_load_lds_dwordx4 v247, s[18:19]
	s_waitcnt vmcnt(6) lgkmcnt(0)
	s_barrier
;   #define CMASK(P0,P1,t) do{int jb_=(t)-tb; if(jb_>=0)cmask(P0,P1,jb_,qrel,hi);}while(0)
;   #define CMASK(P0,P1,t) do{}while(0)
; __device__ __forceinline__ void cmask(f32x16&p0,f32x16&p1,int jb,int qrel,int hi){
;   const float NEG=-INFINITY; int kb=64*jb+4*hi;
;   #pragma unroll
;   for(int r=0;r<16;++r){int kv=kb+(r&3)+8*(r>>2); if(kv>qrel)p0[r]=NEG; if(kv+32>qrel)p1[r]=NEG;}
; }
; __device__ __forceinline__ void glds16(const void*sbase,unsigned voff,unsigned lds_dst){
;   asm volatile("s_mov_b32 m0, %2\n\ts_nop 0\n\tglobal_load_lds_dwordx4 %0, %1"::"v"(voff),"s"(sbase),"s"(lds_dst):"memory","m0");}
; __device__ __forceinline__ float max3f(float a,float b,float c){float r;asm("v_max3_f32 %0, %1, %2, %3":"=v"(r):"v"(a),"v"(b),"v"(c));return r;}
; __device__ __forceinline__ float max2f(float a,float b){float r;asm("v_max_f32_e32 %0, %1, %2":"=v"(r):"v"(a),"v"(b));return r;}
; __device__ __forceinline__ float fadd_s(float a,float b){float r;asm("v_add_f32_e32 %0, %1, %2":"=v"(r):"v"(a),"v"(b));return r;}
; __device__ __forceinline__ float fsub_s(float a,float b){float r;asm("v_sub_f32_e32 %0, %1, %2":"=v"(r):"v"(a),"v"(b));return r;}
; __device__ __forceinline__ unsigned cvtpk_s(float lo,float hi){f32x2_t v={lo,hi};bf16x2_t b=__builtin_convertvector(v,bf16x2_t);return __builtin_bit_cast(unsigned,b);}
; __device__ __forceinline__ void qkt(f32x16&p0,f32x16&p1,const char*Kslot,const bf16x8*qr,int r32,int hi){ const f32x16 negm=f32x16{};
;   const char*kb=Kslot+hi*1024+r32*16;
;   #pragma unroll
;   for(int d0=0;d0<4;++d0){
;     const bf16x8 b0=*reinterpret_cast<const bf16x8*>(kb+d0*2048);
;     const bf16x8 b1=*reinterpret_cast<const bf16x8*>(kb+d0*2048+512);
;     if(d0==0){p0=__builtin_amdgcn_mfma_f32_32x32x16_bf16(b0,qr[0],negm,0,0,0);p1=__builtin_amdgcn_mfma_f32_32x32x16_bf16(b1,qr[0],negm,0,0,0);}
;     else{p0=__builtin_amdgcn_mfma_f32_32x32x16_bf16(b0,qr[d0],p0,0,0,0);p1=__builtin_amdgcn_mfma_f32_32x32x16_bf16(b1,qr[d0],p1,0,0,0);}}
; }
; template<int THRL> __device__ __forceinline__ void attn_unit(int b,int h,float s2,int jq,int t0,const bf16*Q,const bf16*__restrict__ K,const bf16*__restrict__ V,bf16*MIXo,const float*gh,volatile __attribute__((address_space(3))) const float*lamw,char*shm){
;     ...
;   qkt(pA0,pA1,Kbase,qr,r32,hi);asm volatile("s_nop 15\n\ts_nop 7":"+v"(pA0),"+v"(pA1));BIAS(pA0,pA1);CMASK(pA0,pA1,0);
;   START(pA0,pA1);
	v_add3_u32 v249, s22, v239, v2
	ds_read_b128 v[2:5], v249 offset:512
	ds_read_b128 v[6:9], v249
	ds_read_b128 v[36:39], v249 offset:2560
	ds_read_b128 v[40:43], v249 offset:2048
	v_or_b32_e32 v1, s7, v243
	v_cvt_f32_i32_e32 v219, v1
	s_sub_i32 s83, s1, s6
	v_or_b32_e32 v244, s5, v238
	s_cmp_gt_i32 s83, 0
	v_pk_mul_f32 v[216:217], v[214:215], v[218:219] op_sel:[1,0]
	s_waitcnt vmcnt(3) lgkmcnt(2)
	v_mfma_f32_32x32x16_bf16 v[18:33], v[6:9], v[164:167], 0
	v_mfma_f32_32x32x16_bf16 v[2:17], v[2:5], v[164:167], 0
	s_waitcnt vmcnt(2) lgkmcnt(0)
	v_mfma_f32_32x32x16_bf16 v[18:33], v[40:43], v[156:159], v[18:33]
	v_mfma_f32_32x32x16_bf16 v[2:17], v[36:39], v[156:159], v[2:17]
	ds_read_b128 v[36:39], v249 offset:4608
	ds_read_b128 v[40:43], v249 offset:4096
	s_waitcnt vmcnt(1) lgkmcnt(0)
	v_mfma_f32_32x32x16_bf16 v[18:33], v[40:43], v[148:151], v[18:33]
	v_mfma_f32_32x32x16_bf16 v[2:17], v[36:39], v[148:151], v[2:17]
	ds_read_b128 v[36:39], v249 offset:6656
	ds_read_b128 v[40:43], v249 offset:6144
	s_waitcnt vmcnt(0) lgkmcnt(0)
	v_mfma_f32_32x32x16_bf16 v[18:33], v[40:43], v[144:147], v[18:33]
	v_mfma_f32_32x32x16_bf16 v[2:17], v[36:39], v[144:147], v[2:17]
	v_fma_f32 v36, v215, v218, v214
	v_fma_f32 v37, v215, v219, v215
	s_nop 15
	s_nop 7
	v_mov_b32_e32 v38, v217
	v_mov_b32_e32 v39, v37
	s_nop 6
	v_pk_add_f32 v[18:19], v[38:39], v[18:19]
	v_pk_fma_f32 v[38:39], v[214:215], v[218:219], v[216:217] op_sel:[1,0,1] op_sel_hi:[1,1,0]
	v_pk_fma_f32 v[36:37], v[34:35], s[50:51], v[36:37]
	v_pk_add_f32 v[40:41], v[214:215], v[38:39] op_sel:[1,0] op_sel_hi:[0,1]
	v_pk_fma_f32 v[34:35], v[34:35], s[50:51], v[36:37]
	v_mov_b32_e32 v39, v40
	v_mov_b32_e32 v34, v37
	v_pk_add_f32 v[36:37], v[214:215], v[40:41] op_sel:[1,0] op_sel_hi:[0,1]
	v_pk_add_f32 v[2:3], v[38:39], v[2:3]
	v_pk_add_f32 v[38:39], v[214:215], v[36:37] op_sel:[1,0] op_sel_hi:[0,1]
	v_pk_add_f32 v[20:21], v[34:35], v[20:21]
	v_mov_b32_e32 v37, v38
	v_fmac_f32_e32 v35, 0x40a00000, v215
	v_pk_add_f32 v[4:5], v[36:37], v[4:5]
	v_add_f32_e32 v37, v215, v35
	v_fmac_f32_e32 v38, 0x40a00000, v215
	v_add_f32_e32 v34, v215, v37
	v_mov_b32_e32 v36, v35
	v_add_f32_e32 v39, v215, v38
	v_add_f32_e32 v35, v215, v34
	v_pk_add_f32 v[22:23], v[36:37], v[22:23]
	v_pk_add_f32 v[24:25], v[34:35], v[24:25]
	v_add_f32_e32 v36, v215, v39
	v_fmac_f32_e32 v35, 0x40a00000, v215
	v_pk_add_f32 v[6:7], v[38:39], v[6:7]
	v_add_f32_e32 v37, v215, v36
	v_add_f32_e32 v39, v215, v35
	v_pk_add_f32 v[8:9], v[36:37], v[8:9]
	v_fmac_f32_e32 v37, 0x40a00000, v215
	v_add_f32_e32 v36, v215, v39
	v_mov_b32_e32 v38, v35
	v_add_f32_e32 v35, v215, v37
	v_mov_b32_e32 v34, v37
	v_add_f32_e32 v37, v215, v36
	v_pk_add_f32 v[10:11], v[34:35], v[10:11]
	v_pk_add_f32 v[28:29], v[36:37], v[28:29]
	v_add_f32_e32 v34, v215, v35
	v_fmac_f32_e32 v37, 0x40a00000, v215
	v_pk_add_f32 v[26:27], v[38:39], v[26:27]
	v_add_f32_e32 v35, v215, v34
	v_add_f32_e32 v39, v215, v37
	v_pk_add_f32 v[12:13], v[34:35], v[12:13]
	v_fmac_f32_e32 v35, 0x40a00000, v215
	v_add_f32_e32 v34, v215, v39
	v_mov_b32_e32 v38, v37
	v_add_f32_e32 v37, v215, v35
	v_mov_b32_e32 v36, v35
	v_add_f32_e32 v35, v215, v34
	v_pk_add_f32 v[32:33], v[34:35], v[32:33]
	v_add_f32_e32 v34, v215, v37
	v_add_f32_e32 v35, v215, v34
	v_pk_add_f32 v[30:31], v[38:39], v[30:31]
	v_pk_add_f32 v[14:15], v[36:37], v[14:15]
	v_pk_add_f32 v[16:17], v[34:35], v[16:17]
	s_cbranch_scc1 .LBB0_278
	s_lshl_b32 s5, s83, 6
	v_subrev_u32_e32 v1, s5, v243
	v_or_b32_e32 v34, 32, v1
	v_cmp_le_u32_e32 vcc, v34, v244
	v_or_b32_e32 v34, 33, v1
	s_nop 0
	v_cndmask_b32_e32 v2, v229, v2, vcc
	v_cmp_le_u32_e32 vcc, v1, v244
	s_nop 1
	v_cndmask_b32_e32 v18, v229, v18, vcc
	v_cmp_lt_u32_e32 vcc, v1, v244
	s_nop 1
	v_cndmask_b32_e32 v19, v229, v19, vcc
	v_cmp_le_u32_e32 vcc, v34, v244
	v_or_b32_e32 v34, 2, v1
	s_nop 0
	v_cndmask_b32_e32 v3, v229, v3, vcc
	v_cmp_le_u32_e32 vcc, v34, v244
	v_or_b32_e32 v34, 34, v1
	s_nop 0
	v_cndmask_b32_e32 v20, v229, v20, vcc
	v_cmp_le_u32_e32 vcc, v34, v244
	v_or_b32_e32 v34, 3, v1
	s_nop 0
	v_cndmask_b32_e32 v4, v229, v4, vcc
	v_cmp_le_u32_e32 vcc, v34, v244
	v_or_b32_e32 v34, 35, v1
	s_nop 0
	v_cndmask_b32_e32 v21, v229, v21, vcc
	v_cmp_le_u32_e32 vcc, v34, v244
	v_or_b32_e32 v34, 8, v1
	s_nop 0
	v_cndmask_b32_e32 v5, v229, v5, vcc
	v_cmp_le_u32_e32 vcc, v34, v244
	v_or_b32_e32 v34, 40, v1
	s_nop 0
	v_cndmask_b32_e32 v22, v229, v22, vcc
	v_cmp_le_u32_e32 vcc, v34, v244
	v_or_b32_e32 v34, 9, v1
	s_nop 0
	v_cndmask_b32_e32 v6, v229, v6, vcc
	v_cmp_le_u32_e32 vcc, v34, v244
	v_or_b32_e32 v34, 41, v1
	s_nop 0
	v_cndmask_b32_e32 v23, v229, v23, vcc
	v_cmp_le_u32_e32 vcc, v34, v244
	v_or_b32_e32 v34, 10, v1
	s_nop 0
	v_cndmask_b32_e32 v7, v229, v7, vcc
	v_cmp_le_u32_e32 vcc, v34, v244
	v_or_b32_e32 v34, 42, v1
	s_nop 0
	v_cndmask_b32_e32 v24, v229, v24, vcc
	v_cmp_le_u32_e32 vcc, v34, v244
	v_or_b32_e32 v34, 11, v1
	s_nop 0
	v_cndmask_b32_e32 v8, v229, v8, vcc
	v_cmp_le_u32_e32 vcc, v34, v244
	v_or_b32_e32 v34, 43, v1
	s_nop 0
	v_cndmask_b32_e32 v25, v229, v25, vcc
	v_cmp_le_u32_e32 vcc, v34, v244
	v_or_b32_e32 v34, 16, v1
	s_nop 0
	v_cndmask_b32_e32 v9, v229, v9, vcc
	v_cmp_le_u32_e32 vcc, v34, v244
	v_or_b32_e32 v34, 48, v1
	s_nop 0
	v_cndmask_b32_e32 v26, v229, v26, vcc
	v_cmp_le_u32_e32 vcc, v34, v244
	v_or_b32_e32 v34, 17, v1
	s_nop 0
	v_cndmask_b32_e32 v10, v229, v10, vcc
	v_cmp_le_u32_e32 vcc, v34, v244
	v_or_b32_e32 v34, 49, v1
	s_nop 0
	v_cndmask_b32_e32 v27, v229, v27, vcc
	v_cmp_le_u32_e32 vcc, v34, v244
	v_or_b32_e32 v34, 18, v1
	s_nop 0
	v_cndmask_b32_e32 v11, v229, v11, vcc
	v_cmp_le_u32_e32 vcc, v34, v244
	v_or_b32_e32 v34, 50, v1
	s_nop 0
	v_cndmask_b32_e32 v28, v229, v28, vcc
	v_cmp_le_u32_e32 vcc, v34, v244
	v_or_b32_e32 v34, 19, v1
	s_nop 0
	v_cndmask_b32_e32 v12, v229, v12, vcc
	v_cmp_le_u32_e32 vcc, v34, v244
	v_or_b32_e32 v34, 51, v1
	s_nop 0
	v_cndmask_b32_e32 v29, v229, v29, vcc
	v_cmp_le_u32_e32 vcc, v34, v244
	v_or_b32_e32 v34, 24, v1
	s_nop 0
	v_cndmask_b32_e32 v13, v229, v13, vcc
	v_cmp_le_u32_e32 vcc, v34, v244
	v_or_b32_e32 v34, 56, v1
	s_nop 0
	v_cndmask_b32_e32 v30, v229, v30, vcc
	v_cmp_le_u32_e32 vcc, v34, v244
	v_or_b32_e32 v34, 25, v1
	s_nop 0
	v_cndmask_b32_e32 v14, v229, v14, vcc
	v_cmp_le_u32_e32 vcc, v34, v244
	v_or_b32_e32 v34, 57, v1
	s_nop 0
	v_cndmask_b32_e32 v31, v229, v31, vcc
	v_cmp_le_u32_e32 vcc, v34, v244
	v_or_b32_e32 v34, 26, v1
	s_nop 0
	v_cndmask_b32_e32 v15, v229, v15, vcc
	v_cmp_le_u32_e32 vcc, v34, v244
	v_or_b32_e32 v34, 58, v1
	s_nop 0
	v_cndmask_b32_e32 v32, v229, v32, vcc
	v_cmp_le_u32_e32 vcc, v34, v244
	v_or_b32_e32 v34, 27, v1
	v_or_b32_e32 v1, 59, v1
	v_cndmask_b32_e32 v16, v229, v16, vcc
	v_cmp_le_u32_e32 vcc, v34, v244
	s_nop 1
	v_cndmask_b32_e32 v33, v229, v33, vcc
	v_cmp_le_u32_e32 vcc, v1, v244
	s_nop 1
	v_cndmask_b32_e32 v17, v229, v17, vcc

; template<int THRL,class Extra> __device__ __forceinline__ void attn_phase(char*lds,const AttnTensors&T,const unsigned*stats,unsigned*queue,volatile __attribute__((address_space(3))) unsigned*qw,const Extra&X){
;     ...
;   while(idx<N_UNITS+Extra::N){
;     X(idx-N_UNITS);
;     if(threadIdx.x==0)qw[0]=__hip_atomic_fetch_add(queue,1u,__ATOMIC_RELAXED,__HIP_MEMORY_SCOPE_AGENT);
;     asm volatile("s_waitcnt vmcnt(0) lgkmcnt(0)\n\ts_barrier":::"memory");
;     idx=__builtin_amdgcn_readfirstlane((int)qw[0]);
;     asm volatile("s_waitcnt lgkmcnt(0)\n\ts_barrier":::"memory");
;   }
.LBB0_363:
	s_or_b64 exec, exec, s[6:7]
	s_waitcnt vmcnt(0)
	v_readfirstlane_b32 s0, v2
	v_mov_b32_e32 v2, s23
	s_nop 0
	v_add_u32_e32 v1, s0, v1
	s_getreg_b32 s100, hwreg(HW_REG_XCC_ID, 0, 4)
	v_mov_b32_e32 v3, s100
	v_and_b32_e32 v3, 7, v3
	v_lshl_add_u32 v3, v3, 5, v1
	v_lshrrev_b32_e32 v4, 5, v1
	v_lshl_add_u32 v3, v4, 8, v3
	v_add_u32_e32 v1, 0x800, v3
	ds_write_b32 v2, v1

; template<int THRL,class Extra> __device__ __forceinline__ void attn_phase(char*lds,const AttnTensors&T,const unsigned*stats,unsigned*queue,volatile __attribute__((address_space(3))) unsigned*qw,const Extra&X){
;     ...
;     if(threadIdx.x==0)qw[0]=__hip_atomic_fetch_add(queue,1u,__ATOMIC_RELAXED,__HIP_MEMORY_SCOPE_AGENT);
.LBB0_435:
	s_and_saveexec_b64 s[4:5], s[90:91]
	s_cbranch_execz .LBB0_364
	s_mov_b64 s[8:9], exec
	v_mbcnt_lo_u32_b32 v1, s8, 0
	v_mbcnt_hi_u32_b32 v1, s9, v1
	v_cmp_eq_u32_e32 vcc, 0, v1
	s_and_saveexec_b64 s[6:7], vcc
	s_cbranch_execz .LBB0_363
	s_bcnt1_i32_b64 s0, s[8:9]
	v_mov_b32_e32 v2, s0
	global_atomic_add v2, v0, v2, s[54:55] offset:32 sc0
	s_branch .LBB0_363
